# attention loops: packed f32 adds/fma (row sums) split into scalar v_add/v_fma
# speedup vs baseline: 1.0082x; 1.0082x over previous
; #define SBAR() __builtin_amdgcn_sched_barrier(0)
; #define RESC(a) do { if (__any((a) < 1.f)) { if (hi == 0) al_l[r32] = (a); asm volatile("s_waitcnt lgkmcnt(0)" ::: "memory"); \
;     _Pragma("unroll") for (int d = 0; d < 4; ++d) _Pragma("unroll") for (int r = 0; r < 16; ++r) o[d][r] *= al_l[crow(r, hi)]; } } while (0)
; template <int NVT, int VRSB, int KB, int DH, int VT> __device__ __forceinline__ void pvh_pro(int vb, s16x4 (&f)[DH + 1][2]) { if constexpr (VT < DH && VT < NVT) { pvh_ld<VT, KB, VRSB>(f[VT], vb); pvh_pro<NVT, VRSB, KB, DH, VT + 1>(vb, f); } }
; __device__ __forceinline__ void partialSM16(f32x4 (&s)[4][2], float (&m_reg)[2], float (&alpha)[2], const float C, const float thr_s) {
;     ...
;   for (int qt = 0; qt < 2; ++qt) { const float mnC = -mn[qt] * C;
; #pragma unroll
;     for (int kt = 0; kt < 4; ++kt)
; #pragma unroll
;       for (int r = 0; r < 4; ++r) s[kt][qt][r] = fmaf(s[kt][qt][r], C, mnC); }
; #pragma unroll
;   for (int qt = 0; qt < 2; ++qt)
; #pragma unroll
;     for (int kt = 0; kt < 2; ++kt)
; #pragma unroll
;       for (int r = 0; r < 4; ++r) s[kt][qt][r] = __builtin_amdgcn_exp2f(s[kt][qt][r]);
; template <int DK, int DV, int LDQ, int LDK, int LDV, int LDO, typename TOut, bool PIPE, bool QL, bool VS>
; __device__ __forceinline__ void attn_body16(const bf16_t* Qb, const bf16_t* Kh, const bf16_t* Vh, TOut* Ob, int seq, char* lds) {
;     ...
;       partialSM16(s, m_reg, al, C, THR_S);
;       RESC(al);
;       constexpr int DH = 3; s16x4 pvf[DH + 1][2]; const int vbt = vb0 + vsel * (int)SHM_V;
;       pvh_pro<NVT, VRSB, 0, DH, 0>(vbt, pvf); SBAR();
;       cvt_pa(s, pa, 0); SBAR();
;       pvh_step<NVT, VRSB, 0, DH, true, 0>(o, vbt, pa, pvf, s);
.LBB0_676:
	v_mul_f32_e32 v196, 0xbdd53b94, v176
	v_fmamk_f32 v197, v142, 0x3dd53b94, v196
	v_mul_f32_e32 v142, 0xbdd53b94, v175
	v_fmamk_f32 v122, v122, 0x3dd53b94, v142
	v_fmamk_f32 v123, v123, 0x3dd53b94, v142
	s_mulk_i32 s36, 0x4800
	v_fmamk_f32 v213, v151, 0x3dd53b94, v196
	v_fmamk_f32 v124, v124, 0x3dd53b94, v142
	v_fmamk_f32 v125, v125, 0x3dd53b94, v142
	v_fmamk_f32 v222, v149, 0x3dd53b94, v142
	v_exp_f32_e32 v149, v122
	v_exp_f32_e32 v151, v123
	v_add_u32_e32 v223, s36, v174
	ds_read_b64_tr_b16 v[122:123], v223 offset:0
	v_fmamk_f32 v126, v126, 0x3dd53b94, v196
	v_fmamk_f32 v127, v127, 0x3dd53b94, v196
	v_fmamk_f32 v217, v153, 0x3dd53b94, v196
	v_exp_f32_e32 v153, v124
	v_exp_f32_e32 v183, v125
	ds_read_b64_tr_b16 v[124:125], v223 offset:0x1200
	v_fmamk_f32 v128, v128, 0x3dd53b94, v196
	v_fmamk_f32 v129, v129, 0x3dd53b94, v196
	v_fmamk_f32 v212, v150, 0x3dd53b94, v196
	v_fmamk_f32 v221, v148, 0x3dd53b94, v142
	v_exp_f32_e32 v148, v126
	v_exp_f32_e32 v150, v127
	ds_read_b64_tr_b16 v[126:127], v223 offset:32
	v_fmamk_f32 v215, v152, 0x3dd53b94, v196
	v_fmamk_f32 v130, v130, 0x3dd53b94, v142
	v_fmamk_f32 v131, v131, 0x3dd53b94, v142
	v_exp_f32_e32 v152, v128
	v_exp_f32_e32 v182, v129
	ds_read_b64_tr_b16 v[128:129], v223 offset:0x1220
	v_fmamk_f32 v132, v132, 0x3dd53b94, v142
	v_fmamk_f32 v133, v133, 0x3dd53b94, v142
	v_exp_f32_e32 v185, v130
	v_exp_f32_e32 v199, v131
	ds_read_b64_tr_b16 v[130:131], v223 offset:64
	v_exp_f32_e32 v201, v132
	v_exp_f32_e32 v203, v133
	ds_read_b64_tr_b16 v[132:133], v223 offset:0x1240
	v_fmamk_f32 v134, v134, 0x3dd53b94, v196
	v_fmamk_f32 v135, v135, 0x3dd53b94, v196
	v_fmamk_f32 v136, v136, 0x3dd53b94, v196
	v_fmamk_f32 v137, v137, 0x3dd53b94, v196
	s_add_i32 s29, s29, 1
	v_fmamk_f32 v143, v143, 0x3dd53b94, v196
	v_fmamk_f32 v205, v144, 0x3dd53b94, v196
	v_fmamk_f32 v207, v145, 0x3dd53b94, v196
	v_fmamk_f32 v209, v138, 0x3dd53b94, v142
	v_fmamk_f32 v211, v139, 0x3dd53b94, v142
	v_fmamk_f32 v214, v140, 0x3dd53b94, v142
	v_fmamk_f32 v216, v141, 0x3dd53b94, v142
	v_fmamk_f32 v219, v146, 0x3dd53b94, v142
	v_fmamk_f32 v220, v147, 0x3dd53b94, v142
	v_exp_f32_e32 v184, v134
	v_exp_f32_e32 v198, v135
	v_exp_f32_e32 v200, v136
	v_exp_f32_e32 v202, v137
	v_cvt_pk_bf16_f32 v134, v148, v150
	v_cvt_pk_bf16_f32 v135, v152, v182
	v_cvt_pk_bf16_f32 v136, v184, v198
	v_cvt_pk_bf16_f32 v137, v200, v202
	v_cvt_pk_bf16_f32 v138, v149, v151
	v_cvt_pk_bf16_f32 v139, v153, v183
	v_cvt_pk_bf16_f32 v140, v185, v199
	v_cvt_pk_bf16_f32 v141, v201, v203
	ds_read_b64_tr_b16 v[144:145], v223 offset:0x60
	ds_read_b64_tr_b16 v[146:147], v223 offset:0x1260
	s_waitcnt lgkmcnt(6)
	v_mfma_f32_16x16x32_bf16 v[58:61], v[134:137], v[122:125], v[58:61]
	v_exp_f32_e32 v204, v197
	v_exp_f32_e32 v206, v143
	v_mfma_f32_16x16x32_bf16 v[62:65], v[138:141], v[122:125], v[62:65]
	ds_read_b64_tr_b16 v[122:123], v223 offset:0x80
	ds_read_b64_tr_b16 v[124:125], v223 offset:0x1280
	s_waitcnt lgkmcnt(6)
	v_mfma_f32_16x16x32_bf16 v[50:53], v[134:137], v[126:129], v[50:53]
	v_exp_f32_e32 v208, v205
	v_exp_f32_e32 v210, v207
	v_mfma_f32_16x16x32_bf16 v[54:57], v[138:141], v[126:129], v[54:57]
	ds_read_b64_tr_b16 v[126:127], v223 offset:0xa0
	ds_read_b64_tr_b16 v[128:129], v223 offset:0x12a0
	s_waitcnt lgkmcnt(6)
	v_mfma_f32_16x16x32_bf16 v[42:45], v[134:137], v[130:133], v[42:45]
	v_exp_f32_e32 v205, v209
	v_exp_f32_e32 v207, v211
	v_mfma_f32_16x16x32_bf16 v[46:49], v[138:141], v[130:133], v[46:49]
	ds_read_b64_tr_b16 v[130:131], v223 offset:0xc0
	ds_read_b64_tr_b16 v[132:133], v223 offset:0x12c0
	s_waitcnt lgkmcnt(6)
	v_mfma_f32_16x16x32_bf16 v[34:37], v[134:137], v[144:147], v[34:37]
	v_exp_f32_e32 v209, v214
	v_exp_f32_e32 v211, v216
	v_mfma_f32_16x16x32_bf16 v[38:41], v[138:141], v[144:147], v[38:41]
	ds_read_b64_tr_b16 v[144:145], v223 offset:0xe0
	ds_read_b64_tr_b16 v[146:147], v223 offset:0x12e0
	s_waitcnt lgkmcnt(6)
	v_mfma_f32_16x16x32_bf16 v[26:29], v[134:137], v[122:125], v[26:29]
	v_exp_f32_e32 v212, v212
	v_exp_f32_e32 v214, v213
	v_mfma_f32_16x16x32_bf16 v[30:33], v[138:141], v[122:125], v[30:33]
	s_waitcnt lgkmcnt(4)
	v_mfma_f32_16x16x32_bf16 v[18:21], v[134:137], v[126:129], v[18:21]
	v_exp_f32_e32 v216, v215
	v_exp_f32_e32 v218, v217
	v_mfma_f32_16x16x32_bf16 v[22:25], v[138:141], v[126:129], v[22:25]
	s_waitcnt lgkmcnt(2)
; #define SBAR() __builtin_amdgcn_sched_barrier(0)
; template <int NVT, int VRSB, int KB, int DH, int VT> __device__ __forceinline__ void pvh_pro(int vb, s16x4 (&f)[DH + 1][2]) { if constexpr (VT < DH && VT < NVT) { pvh_ld<VT, KB, VRSB>(f[VT], vb); pvh_pro<NVT, VRSB, KB, DH, VT + 1>(vb, f); } }
; #define VWRITE(bv) do { _Pragma("unroll") for (int _q = 0; _q < VP; ++_q) *(bf16x8*)(V_lds + (bv) * SHM_V + VROW(_q) * VRSB + VC8(_q) * 16) = sr_.vs[_q]; } while (0)
; template <int DK, int DV, int LDQ, int LDK, int LDV, int LDO, typename TOut, bool PIPE, bool QL, bool VS>
; __device__ __forceinline__ void attn_body16(const bf16_t* Qb, const bf16_t* Kh, const bf16_t* Vh, TOut* Ob, int seq, char* lds) {
;     ...
;       pvh_step<NVT, VRSB, 0, DH, true, 0>(o, vbt, pa, pvf, s);
;       pvh_pro<NVT, VRSB, 1, DH, 0>(vbt, pvf); SBAR();
; #pragma unroll
;       for (int qt = 0; qt < 2; ++qt) { float ps = 0.f;
; #pragma unroll
;         for (int kt = 0; kt < 4; ++kt) ps += (s[kt][qt][0] + s[kt][qt][1]) + (s[kt][qt][2] + s[kt][qt][3]);
;         lp[qt] = lp[qt] * al[qt] + ps; }
;       cvt_pa(s, pa, 1); SBAR();
;       pvh_step<NVT, VRSB, 1, DH, false, 0>(o, vbt, pa, pvf, s);
;       if constexpr (VS) {
;         asm volatile("s_waitcnt vmcnt(0)" ::: "memory");
;         __syncthreads();
;         if (j + 1 < NT) VWRITE(0);
;       } else if (j + 1 < NT) { asm volatile("s_waitcnt vmcnt(0)" ::: "memory"); VWRITE(bsel ^ 1); }
;       __syncthreads();
	v_mfma_f32_16x16x32_bf16 v[10:13], v[134:137], v[130:133], v[10:13]
	v_exp_f32_e32 v213, v219
	v_exp_f32_e32 v215, v220
	v_mfma_f32_16x16x32_bf16 v[14:17], v[138:141], v[130:133], v[14:17]
	s_waitcnt lgkmcnt(0)
	v_mfma_f32_16x16x32_bf16 v[2:5], v[134:137], v[144:147], v[2:5]
	v_exp_f32_e32 v217, v221
	v_exp_f32_e32 v219, v222
	v_mfma_f32_16x16x32_bf16 v[6:9], v[138:141], v[144:147], v[6:9]
	ds_read_b64_tr_b16 v[122:123], v223 offset:0x2400
	ds_read_b64_tr_b16 v[124:125], v223 offset:0x3600
	ds_read_b64_tr_b16 v[126:127], v223 offset:0x2420
	ds_read_b64_tr_b16 v[128:129], v223 offset:0x3620
	ds_read_b64_tr_b16 v[130:131], v223 offset:0x2440
	ds_read_b64_tr_b16 v[132:133], v223 offset:0x3640
	v_add_f32_e64 v134, v148, v150
	v_add_f32_e64 v135, v149, v151
	v_add_f32_e32 v136, v152, v182
	v_add_f32_e32 v137, v153, v183
	v_add_f32_e32 v138, v184, v198
	v_add_f32_e32 v139, v185, v199
	v_add_f32_e32 v140, v200, v202
	v_add_f32_e32 v141, v201, v203
	v_add_f32_e32 v134, v134, v136
	v_add_f32_e32 v135, v135, v137
	v_add_f32_e32 v136, v138, v140
	v_add_f32_e32 v137, v139, v141
	v_pk_add_f32 v[134:135], v[134:135], 0 op_sel_hi:[1,0]
	v_add_f32_e32 v138, v208, v210
	v_add_f32_e32 v139, v209, v211
	v_add_f32_e32 v134, v136, v134
	v_add_f32_e32 v135, v137, v135
	v_add_f32_e32 v136, v204, v206
	v_add_f32_e32 v137, v205, v207
	v_cvt_pk_bf16_f32 v140, v213, v215
	v_add_f32_e32 v136, v136, v138
	v_add_f32_e32 v137, v137, v139
	v_add_f32_e32 v138, v216, v218
	v_add_f32_e32 v139, v217, v219
	v_add_f32_e32 v134, v136, v134
	v_add_f32_e32 v135, v137, v135
	v_add_f32_e32 v136, v212, v214
	v_add_f32_e32 v137, v213, v215
	v_cvt_pk_bf16_f32 v141, v217, v219
	v_add_f32_e32 v136, v136, v138
	v_add_f32_e32 v137, v137, v139
	v_cvt_pk_bf16_f32 v138, v205, v207
	v_add_f32_e32 v134, v136, v134
	v_add_f32_e32 v135, v137, v135
	v_cvt_pk_bf16_f32 v136, v212, v214
	v_fma_f32 v156, v156, v168, v134
	v_fma_f32 v157, v157, v169, v135
	v_cvt_pk_bf16_f32 v134, v204, v206
	v_cvt_pk_bf16_f32 v135, v208, v210
	v_cvt_pk_bf16_f32 v137, v216, v218
	v_cvt_pk_bf16_f32 v139, v209, v211
	ds_read_b64_tr_b16 v[144:145], v223 offset:0x2460
	ds_read_b64_tr_b16 v[146:147], v223 offset:0x3660
	s_waitcnt lgkmcnt(6)
	s_nop 0
	v_mfma_f32_16x16x32_bf16 v[58:61], v[134:137], v[122:125], v[58:61]
	v_mfma_f32_16x16x32_bf16 v[62:65], v[138:141], v[122:125], v[62:65]
	ds_read_b64_tr_b16 v[122:123], v223 offset:0x2480
	ds_read_b64_tr_b16 v[124:125], v223 offset:0x3680
	s_waitcnt lgkmcnt(6)
	v_mfma_f32_16x16x32_bf16 v[50:53], v[134:137], v[126:129], v[50:53]
	v_mfma_f32_16x16x32_bf16 v[54:57], v[138:141], v[126:129], v[54:57]
	ds_read_b64_tr_b16 v[126:127], v223 offset:0x24a0
	ds_read_b64_tr_b16 v[128:129], v223 offset:0x36a0
	s_waitcnt lgkmcnt(6)
	v_mfma_f32_16x16x32_bf16 v[42:45], v[134:137], v[130:133], v[42:45]
	v_mfma_f32_16x16x32_bf16 v[46:49], v[138:141], v[130:133], v[46:49]
	ds_read_b64_tr_b16 v[130:131], v223 offset:0x24c0
	ds_read_b64_tr_b16 v[132:133], v223 offset:0x36c0
	s_waitcnt lgkmcnt(6)
	v_mfma_f32_16x16x32_bf16 v[34:37], v[134:137], v[144:147], v[34:37]
	v_mfma_f32_16x16x32_bf16 v[38:41], v[138:141], v[144:147], v[38:41]
	ds_read_b64_tr_b16 v[144:145], v223 offset:0x24e0
	ds_read_b64_tr_b16 v[146:147], v223 offset:0x36e0
	s_waitcnt lgkmcnt(6)
	v_mfma_f32_16x16x32_bf16 v[26:29], v[134:137], v[122:125], v[26:29]
	v_mfma_f32_16x16x32_bf16 v[30:33], v[138:141], v[122:125], v[30:33]
	s_waitcnt lgkmcnt(4)
	v_mfma_f32_16x16x32_bf16 v[18:21], v[134:137], v[126:129], v[18:21]
	v_mfma_f32_16x16x32_bf16 v[22:25], v[138:141], v[126:129], v[22:25]
	s_waitcnt lgkmcnt(2)
	v_mfma_f32_16x16x32_bf16 v[10:13], v[134:137], v[130:133], v[10:13]
	v_mfma_f32_16x16x32_bf16 v[14:17], v[138:141], v[130:133], v[14:17]
	s_waitcnt lgkmcnt(0)
	v_mfma_f32_16x16x32_bf16 v[2:5], v[134:137], v[144:147], v[2:5]
	v_mfma_f32_16x16x32_bf16 v[6:9], v[138:141], v[144:147], v[6:9]
	s_mulk_i32 s33, 0x4800
	s_waitcnt vmcnt(0)
	s_add_i32 s6, s33, 0
	v_add3_u32 v122, s6, v187, v177
	s_waitcnt vmcnt(0)
	ds_write_b128 v122, v[118:121]
	v_add3_u32 v118, s6, v188, v186
	s_add_u32 s52, s52, s80
	s_addc_u32 s53, s53, s81
	s_add_u32 s54, s54, s96
	s_addc_u32 s55, s55, s97
	s_cmp_eq_u32 s30, s29
	ds_write_b128 v118, v[114:117]
	s_waitcnt lgkmcnt(0)
	s_barrier
	s_cbranch_scc1 .LBB0_683

; #define SBAR() __builtin_amdgcn_sched_barrier(0)
; #define VWRITE(bv) do { _Pragma("unroll") for (int _q = 0; _q < VP; ++_q) *(bf16x8*)(V_lds + (bv) * SHM_V + VROW(_q) * VRSB + VC8(_q) * 16) = sr_.vs[_q]; } while (0)
; template <int DK, int DV, int LDQ, int LDK, int LDV, int LDO, typename TOut, bool PIPE, bool QL, bool VS>
; __device__ __forceinline__ void attn_body16(const bf16_t* Qb, const bf16_t* Kh, const bf16_t* Vh, TOut* Ob, int seq, char* lds) {
;     ...
; #pragma unroll
;       for (int qt = 0; qt < 2; ++qt) { float ps = 0.f;
; #pragma unroll
;         for (int kt = 0; kt < 4; ++kt) ps += (s[kt][qt][0] + s[kt][qt][1]) + (s[kt][qt][2] + s[kt][qt][3]);
;         lp[qt] = lp[qt] * al[qt] + ps; }
;       cvt_pa(s, pa, 1); SBAR();
;       pvh_step<NVT, VRSB, 1, DH, false, 0>(o, vbt, pa, pvf, s);
;       if constexpr (VS) {
;         asm volatile("s_waitcnt vmcnt(0)" ::: "memory");
;         __syncthreads();
;         if (j + 1 < NT) VWRITE(0);
;       } else if (j + 1 < NT) { asm volatile("s_waitcnt vmcnt(0)" ::: "memory"); VWRITE(bsel ^ 1); }
;       __syncthreads();
.LBB0_699:
	v_add_f32_e32 v146, v166, v168
	v_add_f32_e32 v147, v167, v169
	v_add_f32_e32 v148, v162, v164
	v_add_f32_e32 v149, v163, v165
	v_add_f32_e32 v150, v158, v160
	v_add_f32_e32 v151, v159, v161
	v_add_f32_e32 v152, v154, v156
	v_add_f32_e32 v153, v155, v157
	v_add_f32_e32 v146, v146, v148
	v_add_f32_e32 v147, v147, v149
	v_add_f32_e32 v148, v150, v152
	v_add_f32_e32 v149, v151, v153
	v_pk_add_f32 v[146:147], v[146:147], 0 op_sel_hi:[1,0]
	v_add_f32_e32 v150, v174, v176
	v_add_f32_e32 v151, v175, v177
	v_add_f32_e32 v146, v148, v146
	v_add_f32_e32 v147, v149, v147
	v_add_f32_e32 v148, v170, v172
	v_add_f32_e32 v149, v171, v173
	s_add_u32 s10, s10, 0xc2000
	v_add_f32_e32 v148, v148, v150
	v_add_f32_e32 v149, v149, v151
	v_add_f32_e32 v150, v208, v210
	v_add_f32_e32 v151, v209, v211
	v_add_f32_e32 v146, v148, v146
	v_add_f32_e32 v147, v149, v147
	v_add_f32_e32 v148, v204, v206
	v_add_f32_e32 v149, v205, v207
	s_addc_u32 s11, s11, 0
	v_add_f32_e32 v148, v148, v150
	v_add_f32_e32 v149, v149, v151
	s_add_i32 s29, s29, 1
	v_add_f32_e32 v146, v148, v146
	v_add_f32_e32 v147, v149, v147
	s_mul_i32 s6, s28, 0xc2000
	v_fma_f32 v196, v196, v202, v146
	v_fma_f32 v197, v197, v203, v147
	s_cmp_eq_u32 s6, s10
	s_waitcnt lgkmcnt(0)
	s_barrier
	s_cbranch_scc1 .LBB0_713
